# work-queue counters sharded 16 ways (32 contenders per counter), ring of 2 counter sets
# speedup vs baseline: 1.0030x; 1.0009x over previous
.LBB0_5:
	s_ashr_i32 s15, s14, 31
	s_lshl_b64 s[0:1], s[14:15], 2
	v_readlane_b32 s2, v253, 23
	s_add_u32 s2, s2, s0
	v_readlane_b32 s0, v253, 24
	s_addc_u32 s3, s0, s1
	v_writelane_b32 v254, s2, 43
	s_mov_b32 s0, s14
	s_mov_b32 s28, 0x18000
	v_writelane_b32 v254, s3, 44
	v_writelane_b32 v254, s0, 45
	s_mov_b64 s[4:5], -1
	s_mov_b64 s[2:3], 0
	v_writelane_b32 v254, s1, 46
	s_mov_b32 s98, 1
	s_nop 0
	v_writelane_b32 v255, s98, 14
	s_and_b32 s98, s14, 1
	s_nop 0
	s_nop 0
	v_readlane_b32 s99, v254, 20
	s_and_b32 s99, s99, 15
	s_lshl_b32 s98, s98, 4
	s_add_i32 s98, s98, s99
	s_lshl_b32 s98, s98, 7
	s_add_i32 s98, s98, 0x3000
	v_readlane_b32 s0, v253, 17
	v_readlane_b32 s1, v253, 18
	s_add_u32 s0, s0, s98
	s_addc_u32 s1, s1, 0
	s_nop 0
	v_writelane_b32 v254, s0, 43
	v_writelane_b32 v254, s1, 44
	v_readlane_b32 s99, v254, 20
	s_cmp_lg_u32 s99, 0
	s_cbranch_scc1 .Lsh_skip
	s_add_i32 s98, s14, 1
	s_and_b32 s98, s98, 1
	s_nop 0
	s_nop 0
	s_lshl_b32 s98, s98, 11
	s_add_i32 s98, s98, 0x3000
	v_readlane_b32 s0, v253, 17
	v_readlane_b32 s1, v253, 18
	s_add_u32 s0, s0, s98
	s_addc_u32 s1, s1, 0
	s_and_saveexec_b64 s[98:99], s[12:13]
	global_store_dword v131, v131, s[0:1] sc1
	global_store_dword v131, v131, s[0:1] offset:128 sc1
	global_store_dword v131, v131, s[0:1] offset:256 sc1
	global_store_dword v131, v131, s[0:1] offset:384 sc1
	global_store_dword v131, v131, s[0:1] offset:512 sc1
	global_store_dword v131, v131, s[0:1] offset:640 sc1
	global_store_dword v131, v131, s[0:1] offset:768 sc1
	global_store_dword v131, v131, s[0:1] offset:896 sc1
	global_store_dword v131, v131, s[0:1] offset:1024 sc1
	global_store_dword v131, v131, s[0:1] offset:1152 sc1
	global_store_dword v131, v131, s[0:1] offset:1280 sc1
	global_store_dword v131, v131, s[0:1] offset:1408 sc1
	global_store_dword v131, v131, s[0:1] offset:1536 sc1
	global_store_dword v131, v131, s[0:1] offset:1664 sc1
	global_store_dword v131, v131, s[0:1] offset:1792 sc1
	global_store_dword v131, v131, s[0:1] offset:1920 sc1
	s_or_b64 exec, exec, s[98:99]

.LBB0_24:
	s_or_b64 exec, exec, s[0:1]
	s_waitcnt lgkmcnt(0)
	s_barrier
	ds_read_b32 v1, v161
	s_waitcnt lgkmcnt(0)
	v_readfirstlane_b32 s10, v1
	v_readlane_b32 s98, v255, 14
	s_cmp_eq_u32 s98, 0
	s_cbranch_scc0 .Lsdp1_first
	v_readlane_b32 s98, v254, 20
	s_and_b32 s98, s98, 15
	s_lshl_b32 s10, s10, 4
	s_add_i32 s10, s10, s98
	v_readlane_b32 s99, v255, 13
	s_sub_i32 s99, s99, s98
	s_add_i32 s99, s99, 15
	s_and_b32 s99, s99, -16
	s_add_i32 s10, s10, s99

.LBB0_72:
	s_or_b64 exec, exec, s[0:1]
	s_waitcnt lgkmcnt(0)
	s_barrier
	ds_read_b32 v1, v161
	s_waitcnt lgkmcnt(0)
	v_readfirstlane_b32 s0, v1
	v_readlane_b32 s98, v254, 20
	s_and_b32 s98, s98, 15
	s_lshl_b32 s0, s0, 4
	s_add_i32 s0, s0, s98
	v_readlane_b32 s99, v255, 13
	s_sub_i32 s99, s99, s98
	s_add_i32 s99, s99, 15
	s_and_b32 s99, s99, -16
	s_add_i32 s0, s0, s99
	s_cmp_ge_i32 s0, s14
	s_cbranch_scc1 .LBB0_117

.LBB0_173:
	s_or_b64 exec, exec, s[0:1]
	s_waitcnt lgkmcnt(0)
	s_barrier
	ds_read_b32 v1, v161
	s_waitcnt lgkmcnt(0)
	v_readfirstlane_b32 s20, v1
	v_readlane_b32 s98, v254, 20
	s_and_b32 s98, s98, 15
	s_lshl_b32 s20, s20, 4
	s_add_i32 s20, s20, s98
	v_readlane_b32 s99, v255, 13
	s_sub_i32 s99, s99, s98
	s_add_i32 s99, s99, 15
	s_and_b32 s99, s99, -16
	s_add_i32 s20, s20, s99
	s_cmp_ge_i32 s20, s18
	s_cbranch_scc1 .LBB0_287

.LBB0_295:
	s_or_b64 exec, exec, s[2:3]
	s_waitcnt lgkmcnt(0)
	s_barrier
	ds_read_b32 v1, v161
	s_waitcnt lgkmcnt(0)
	v_readfirstlane_b32 s14, v1
	v_readlane_b32 s98, v254, 20
	s_and_b32 s98, s98, 15
	s_lshl_b32 s14, s14, 4
	s_add_i32 s14, s14, s98
	v_readlane_b32 s99, v255, 13
	s_sub_i32 s99, s99, s98
	s_add_i32 s99, s99, 15
	s_and_b32 s99, s99, -16
	s_add_i32 s14, s14, s99
	s_cmpk_gt_i32 s14, 0x83f
	s_cbranch_scc1 .LBB0_398

.LBB0_409:
	s_or_b64 exec, exec, s[0:1]
	s_waitcnt lgkmcnt(0)
	s_barrier
	ds_read_b32 v1, v161
	s_waitcnt lgkmcnt(0)
	v_readfirstlane_b32 s2, v1
	v_readlane_b32 s98, v254, 20
	s_and_b32 s98, s98, 15
	s_lshl_b32 s2, s2, 4
	s_add_i32 s2, s2, s98
	v_readlane_b32 s99, v255, 13
	s_sub_i32 s99, s99, s98
	s_add_i32 s99, s99, 15
	s_and_b32 s99, s99, -16
	s_add_i32 s2, s2, s99
	s_cmpk_gt_i32 s2, 0x113f
	s_cbranch_scc1 .LBB0_447

.LBB0_456:
	s_or_b64 exec, exec, s[0:1]
	s_waitcnt lgkmcnt(0)
	s_barrier
	ds_read_b32 v1, v161
	s_waitcnt lgkmcnt(0)
	v_readfirstlane_b32 s21, v1
	v_readlane_b32 s98, v254, 20
	s_and_b32 s98, s98, 15
	s_lshl_b32 s21, s21, 4
	s_add_i32 s21, s21, s98
	v_readlane_b32 s99, v255, 13
	s_sub_i32 s99, s99, s98
	s_add_i32 s99, s99, 15
	s_and_b32 s99, s99, -16
	s_add_i32 s21, s21, s99
	s_cmp_ge_i32 s21, s17
	s_cbranch_scc1 .LBB0_559

.LBB0_570:
	s_or_b64 exec, exec, s[4:5]
	s_waitcnt lgkmcnt(0)
	s_barrier
	ds_read_b32 v1, v161
	v_readlane_b32 s0, v254, 49
	s_waitcnt lgkmcnt(0)
	v_readfirstlane_b32 s18, v1
	v_readlane_b32 s98, v254, 20
	s_and_b32 s98, s98, 15
	s_lshl_b32 s18, s18, 4
	s_add_i32 s18, s18, s98
	v_readlane_b32 s99, v255, 13
	s_sub_i32 s99, s99, s98
	s_add_i32 s99, s99, 15
	s_and_b32 s99, s99, -16
	s_add_i32 s18, s18, s99
	s_cmp_ge_i32 s18, s0
	s_cbranch_scc1 .LBB0_740

.LBB0_876:
	s_or_b64 exec, exec, s[0:1]
	s_waitcnt lgkmcnt(0)
	s_barrier
	ds_read_b32 v1, v161
	s_waitcnt lgkmcnt(0)
	v_readfirstlane_b32 s18, v1
	v_readlane_b32 s98, v255, 14
	s_cmp_eq_u32 s98, 0
	s_cbranch_scc0 .Lsdp0_first
	v_readlane_b32 s98, v254, 20
	s_and_b32 s98, s98, 15
	s_lshl_b32 s18, s18, 4
	s_add_i32 s18, s18, s98
	v_readlane_b32 s99, v255, 13
	s_sub_i32 s99, s99, s98
	s_add_i32 s99, s99, 15
	s_and_b32 s99, s99, -16
	s_add_i32 s18, s18, s99
